# up-GEMM phase start: the four per-row 1/rms partial loads for the LDS table are issued together (one wait) instead of four load-wait round trips
# speedup vs baseline: 1.0013x; 1.0004x over previous
; __device__ __forceinline__ float row_rs(const float* RSP, int row) { const f32x4 p = *(const f32x4*)(RSP + (size_t)row * 4); return rsqrtf(((p[0] + p[1]) + (p[2] + p[3])) * (1.0f / DM) + RMS_EPS); }
; __global__ void __launch_bounds__(NTHR, 2) fwd_megakernel(Args kargs) {
;     ...
;                 LAS float* rsl = (LAS float*)(lds + 131072);
;                 { const int nwg = 256 * 22, q8 = nwg / 8, wg0 = (bx % 8) * q8 + bx / 8, off = (wg0 % 176) % 8;
; #pragma unroll
;                   for (int k = 0; k < 4; ++k) { const int pmk = 8 * ((bx % 8) * 4 + k) + off; if (tid < 256) rsl[k * 256 + tid] = row_rs(RS, pmk * 256 + tid); } }
;                 __syncthreads();
.LBB0_1200:
	v_readlane_b32 s0, v255, 19
	s_waitcnt lgkmcnt(0)
	s_or_b32 s44, s77, s0
	s_cmp_ge_i32 s26, s86
	s_cselect_b64 s[0:1], -1, 0
	s_cmp_lt_i32 s26, s87
	s_cselect_b64 s[8:9], -1, 0
	s_and_b64 s[8:9], s[0:1], s[8:9]
	s_andn2_b64 vcc, exec, s[8:9]
	s_cbranch_vccnz .LBB0_1227
	s_mov_b64 s[8:9], s[82:83]
	v_mov_b32_e32 v0, v202
	s_load_dwordx2 s[10:11], s[8:9], 0xb8
	s_movk_i32 s8, 0x100
	v_cmp_gt_i32_e32 vcc, s8, v0
	s_and_saveexec_b64 s[8:9], vcc
	s_cbranch_execz .LBB0_1203
	v_readlane_b32 s14, v254, 16
	s_waitcnt lgkmcnt(0)
	s_add_u32 s12, s10, 0x36604000
	v_lshl_add_u32 v2, v0, 2, 0
	v_add_u32_e32 v6, s14, v0
	s_addc_u32 s13, s11, 0
	v_ashrrev_i32_e32 v7, 31, v6
	v_add_u32_e32 v12, 0x20000, v2
	v_lshl_add_u64 v[56:57], v[6:7], 4, s[12:13]
	global_load_dwordx4 v[40:43], v[56:57], off
	v_add_u32_e32 v56, 0x800, v6
	v_ashrrev_i32_e32 v57, 31, v56
	v_lshl_add_u64 v[56:57], v[56:57], 4, s[12:13]
	global_load_dwordx4 v[44:47], v[56:57], off
	v_add_u32_e32 v56, 0x1000, v6
	v_ashrrev_i32_e32 v57, 31, v56
	v_lshl_add_u64 v[56:57], v[56:57], 4, s[12:13]
	global_load_dwordx4 v[48:51], v[56:57], off
	v_add_u32_e32 v56, 0x1800, v6
	v_ashrrev_i32_e32 v57, 31, v56
	v_lshl_add_u64 v[56:57], v[56:57], 4, s[12:13]
	global_load_dwordx4 v[52:55], v[56:57], off
	s_waitcnt vmcnt(0)
	v_lshl_add_u64 v[2:3], v[6:7], 4, s[12:13]
	v_mov_b32_e32 v2, v40
	v_mov_b32_e32 v3, v41
	v_mov_b32_e32 v4, v42
	v_mov_b32_e32 v5, v43
	s_mov_b32 s14, 0x358637bd
	s_mov_b32 s16, 0x3a800000
	s_waitcnt vmcnt(0)
	v_mov_b32_e32 v8, v3
	v_mov_b32_e32 v9, v4
	v_mov_b32_e32 v3, v5
	v_pk_add_f32 v[8:9], v[8:9], v[2:3]
	v_add_u32_e32 v2, 0x800, v6
	v_ashrrev_i32_e32 v3, 31, v2
	v_lshl_add_u64 v[2:3], v[2:3], 4, s[12:13]
	v_mov_b32_e32 v2, v44
	v_mov_b32_e32 v3, v45
	v_mov_b32_e32 v4, v46
	v_mov_b32_e32 v5, v47
	s_waitcnt vmcnt(0)
	v_mov_b32_e32 v10, v3
	v_mov_b32_e32 v11, v4
	v_mov_b32_e32 v3, v5
	v_pk_add_f32 v[2:3], v[10:11], v[2:3]
	v_mov_b32_e32 v5, v8
	v_mov_b32_e32 v4, v2
	v_mov_b32_e32 v8, v3
	v_pk_add_f32 v[2:3], v[4:5], v[8:9]
	v_mov_b64_e32 v[8:9], s[14:15]
	v_pk_fma_f32 v[2:3], v[2:3], s[16:17], v[8:9] op_sel_hi:[1,0,0]
	s_mov_b32 s14, 0x800000
	v_mul_f32_e32 v0, 0x4b800000, v3
	v_cmp_gt_f32_e64 s[42:43], s14, v3
	v_cmp_gt_f32_e32 vcc, s14, v2
	s_nop 0
	v_cndmask_b32_e64 v0, v3, v0, s[42:43]
	v_rsq_f32_e32 v0, v0
	s_nop 0
	v_mul_f32_e32 v3, 0x45800000, v0
	v_cndmask_b32_e64 v0, v0, v3, s[42:43]
	v_mul_f32_e32 v3, 0x4b800000, v2
	v_cndmask_b32_e32 v2, v2, v3, vcc
	v_rsq_f32_e32 v2, v2
	s_nop 0
	v_mul_f32_e32 v3, 0x45800000, v2
	v_cndmask_b32_e32 v2, v2, v3, vcc
	ds_write2st64_b32 v12, v0, v2 offset1:4
	v_add_u32_e32 v2, 0x1000, v6
	v_ashrrev_i32_e32 v3, 31, v2
	v_lshl_add_u64 v[2:3], v[2:3], 4, s[12:13]
	v_mov_b32_e32 v2, v48
	v_mov_b32_e32 v3, v49
	v_mov_b32_e32 v4, v50
	v_mov_b32_e32 v5, v51
	s_waitcnt vmcnt(0)
	v_mov_b32_e32 v10, v3
	v_mov_b32_e32 v11, v4
	v_mov_b32_e32 v3, v5
	v_pk_add_f32 v[10:11], v[10:11], v[2:3]
	v_add_u32_e32 v2, 0x1800, v6
	v_ashrrev_i32_e32 v3, 31, v2
	v_lshl_add_u64 v[2:3], v[2:3], 4, s[12:13]
	v_mov_b32_e32 v2, v52
	v_mov_b32_e32 v3, v53
	v_mov_b32_e32 v4, v54
	v_mov_b32_e32 v5, v55
	s_waitcnt vmcnt(0)
	v_mov_b32_e32 v6, v3
	v_mov_b32_e32 v7, v4
	v_mov_b32_e32 v3, v5
	v_pk_add_f32 v[2:3], v[6:7], v[2:3]
	v_mov_b32_e32 v5, v10
	v_mov_b32_e32 v4, v2
	v_mov_b32_e32 v10, v3
	v_pk_add_f32 v[2:3], v[4:5], v[10:11]
	s_nop 0
	v_pk_fma_f32 v[2:3], v[2:3], s[16:17], v[8:9] op_sel_hi:[1,0,0]
	s_nop 0
	v_mul_f32_e32 v0, 0x4b800000, v3
	v_cmp_gt_f32_e64 s[42:43], s14, v3
	v_cmp_gt_f32_e32 vcc, s14, v2
	s_nop 0
	v_cndmask_b32_e64 v0, v3, v0, s[42:43]
	v_rsq_f32_e32 v0, v0
	s_nop 0
	v_mul_f32_e32 v3, 0x45800000, v0
	v_cndmask_b32_e64 v0, v0, v3, s[42:43]
	v_mul_f32_e32 v3, 0x4b800000, v2
	v_cndmask_b32_e32 v2, v2, v3, vcc
	v_rsq_f32_e32 v2, v2
	s_nop 0
	v_mul_f32_e32 v3, 0x45800000, v2
	v_cndmask_b32_e32 v2, v2, v3, vcc
	ds_write2st64_b32 v12, v0, v2 offset0:8 offset1:12
